# w_o and down fused epilogues: the row's four partial-sum slots polled together (two 16-byte loads) instead of four dependent round trips
# speedup vs baseline: 1.0058x; 1.0058x over previous
.LBB0_814:
	s_or_b64 exec, exec, s[8:9]
	s_movk_i32 s1, 0x100
	v_cmp_gt_i32_e64 s[8:9], s1, v178
	s_movk_i32 s1, 0xff
	v_cmp_lt_i32_e32 vcc, s1, v178
	s_waitcnt vmcnt(0) lgkmcnt(0)
	s_barrier
	s_and_saveexec_b64 s[12:13], vcc
	s_xor_b64 s[12:13], exec, s[12:13]
	s_lshl_b32 s1, s0, 8
	s_or_saveexec_b64 s[12:13], s[12:13]
	v_mov_b32_e32 v181, s1
	v_add_u32_e32 v136, 0, v149
	s_xor_b64 exec, exec, s[12:13]
	s_cbranch_execz .LBB0_850
	ds_read_b128 v[128:131], v136
	s_lshl_b32 s29, s0, 8
	v_add_u32_e32 v132, s29, v178
	v_ashrrev_i32_e32 v133, 31, v132
	v_readlane_b32 s40, v252, 0
	s_waitcnt lgkmcnt(0)
	v_mov_b32_e32 v134, v129
	v_mov_b32_e32 v135, v130
	v_mov_b32_e32 v129, v131
	v_pk_add_f32 v[128:129], v[134:135], v[128:129]
	v_readlane_b32 s46, v252, 6
	v_pk_add_f32 v[130:131], v[128:129], v[128:129] op_sel:[0,1] op_sel_hi:[1,0]
	v_lshlrev_b64 v[128:129], 5, v[132:133]
	v_readlane_b32 s47, v252, 7
	s_mov_b64 s[0:1], 0xe420000
	s_ashr_i32 s11, s10, 31
	v_lshl_add_u64 v[128:129], s[46:47], 0, v[128:129]
	v_lshl_add_u64 v[128:129], v[128:129], 0, s[0:1]
	v_lshl_add_u64 v[132:133], s[10:11], 3, v[128:129]
	v_mov_b32_e32 v131, 1
	global_store_dwordx2 v[132:133], v[130:131], off sc1
	v_readlane_b32 s60, v252, 11
	v_readlane_b32 s61, v252, 12
	v_mov_b32_e32 v160, 0
	s_add_u32 s60, s60, 0x10000
	s_addc_u32 s61, s61, 0
	global_load_dword v161, v160, s[60:61] sc1
	s_mov_b32 s11, 0
.Lxch_wo_poll:
	global_load_dwordx4 v[152:155], v[128:129], off sc1
	global_load_dwordx4 v[156:159], v[128:129], off offset:16 sc1
	s_waitcnt vmcnt(0)
	v_min3_u32 v162, v153, v155, v157
	v_min_u32_e32 v162, v162, v159
	v_cmp_eq_u32_e32 vcc, 0, v162
	s_cbranch_vccz .Lxch_wo_ready
	s_add_i32 s11, s11, 1
	s_cmp_lt_u32 s11, 0x400000
	s_cbranch_scc0 .Lxch_wo_ready
	s_sleep 1
	s_branch .Lxch_wo_poll
.Lxch_wo_ready:
	v_mov_b32_e32 v132, v152
	v_mov_b32_e32 v133, v154
	v_mov_b32_e32 v134, v156
	v_mov_b32_e32 v138, v158
	v_add_f32_e32 v128, 0, v132
	v_add_f32_e32 v128, v128, v133
	v_add_f32_e32 v128, v128, v134
	v_add_f32_e32 v128, v128, v138
	v_mov_b32_e32 v129, 0x358637bd
	v_fmac_f32_e32 v129, 0x3a800000, v128
	s_mov_b32 s0, 0xf800000
	v_mul_f32_e32 v128, 0x4f800000, v129
	v_cmp_gt_f32_e32 vcc, s0, v129
	v_mov_b32_e32 v181, s29
	s_nop 0
	v_cndmask_b32_e32 v128, v129, v128, vcc
	v_sqrt_f32_e32 v129, v128
	s_nop 0
	v_add_u32_e32 v130, -1, v129
	v_fma_f32 v131, -v130, v129, v128
	v_cmp_ge_f32_e64 s[0:1], 0, v131
	v_add_u32_e32 v131, 1, v129
	s_nop 0
	v_cndmask_b32_e64 v130, v129, v130, s[0:1]
	v_fma_f32 v129, -v131, v129, v128
	v_cmp_lt_f32_e64 s[0:1], 0, v129
	s_nop 1
	v_cndmask_b32_e64 v129, v130, v131, s[0:1]
	v_mul_f32_e32 v130, 0x37800000, v129
	v_cndmask_b32_e32 v129, v129, v130, vcc
	v_mov_b32_e32 v130, 0x260
	v_cmp_class_f32_e32 vcc, v128, v130
	s_nop 1
	v_cndmask_b32_e32 v128, v129, v128, vcc
	v_div_scale_f32 v129, s[0:1], v128, v128, 1.0
	v_rcp_f32_e32 v130, v129
	s_nop 0
	v_fma_f32 v131, -v129, v130, 1.0
	v_fmac_f32_e32 v130, v131, v130
	v_div_scale_f32 v131, vcc, 1.0, v128, 1.0
	v_mul_f32_e32 v132, v131, v130
	v_fma_f32 v133, -v129, v132, v131
	v_fmac_f32_e32 v132, v133, v130
	v_fma_f32 v129, -v129, v132, v131
	v_div_fmas_f32 v129, v129, v130, v132
	v_div_fixup_f32 v130, v129, v128, 1.0
	v_mad_u64_u32 v[128:129], s[0:1], v178, -12, v[136:137]
	ds_write_b32 v128, v130 offset:8192
	s_mov_b32 s16, 0

.LBB0_1181:
	s_or_b64 exec, exec, s[0:1]
	s_movk_i32 s0, 0xff
	v_cmp_lt_i32_e32 vcc, s0, v148
	s_waitcnt vmcnt(0) lgkmcnt(0)
	s_barrier
	s_and_saveexec_b64 s[0:1], vcc
	s_xor_b64 s[0:1], exec, s[0:1]
	s_lshl_b32 s11, s12, 8
	s_or_saveexec_b64 s[6:7], s[0:1]
	v_mov_b32_e32 v128, s11
	s_xor_b64 exec, exec, s[6:7]
	s_cbranch_execz .LBB0_1217
	v_add_u32_e32 v128, 0, v151
	ds_read_b128 v[130:133], v128
	s_lshl_b32 s20, s12, 8
	v_add_u32_e32 v134, s20, v148
	v_ashrrev_i32_e32 v135, 31, v134
	v_readlane_b32 s12, v252, 0
	s_waitcnt lgkmcnt(0)
	v_mov_b32_e32 v136, v131
	v_mov_b32_e32 v137, v132
	v_mov_b32_e32 v131, v133
	v_pk_add_f32 v[130:131], v[136:137], v[130:131]
	v_readlane_b32 s18, v252, 6
	v_pk_add_f32 v[132:133], v[130:131], v[130:131] op_sel:[0,1] op_sel_hi:[1,0]
	v_lshlrev_b64 v[130:131], 5, v[134:135]
	v_readlane_b32 s19, v252, 7
	s_mov_b64 s[0:1], 0xe3a0000
	s_ashr_i32 s11, s10, 31
	v_lshl_add_u64 v[130:131], s[18:19], 0, v[130:131]
	v_lshl_add_u64 v[130:131], v[130:131], 0, s[0:1]
	v_readlane_b32 s13, v252, 1
	v_lshl_add_u64 v[134:135], s[10:11], 3, v[130:131]
	v_mov_b32_e32 v133, 1
	global_store_dwordx2 v[134:135], v[132:133], off sc1
	v_readlane_b32 s60, v252, 11
	v_readlane_b32 s61, v252, 12
	v_mov_b32_e32 v160, 0
	s_add_u32 s60, s60, 0x11000
	s_addc_u32 s61, s61, 0
	global_load_dword v161, v160, s[60:61] sc1
	s_mov_b32 s11, 0
.Lxch_dn_poll:
	global_load_dwordx4 v[162:165], v[130:131], off sc1
	global_load_dwordx4 v[166:169], v[130:131], off offset:16 sc1
	s_waitcnt vmcnt(0)
	v_min3_u32 v170, v163, v165, v167
	v_min_u32_e32 v170, v170, v169
	v_cmp_eq_u32_e32 vcc, 0, v170
	s_cbranch_vccz .Lxch_dn_ready
	s_add_i32 s11, s11, 1
	s_cmp_lt_u32 s11, 0x400000
	s_cbranch_scc0 .Lxch_dn_ready
	s_sleep 1
	s_branch .Lxch_dn_poll
.Lxch_dn_ready:
	v_mov_b32_e32 v129, v162
	v_mov_b32_e32 v134, v164
	v_mov_b32_e32 v135, v166
	v_mov_b32_e32 v137, v168
	s_mov_b32 s16, 0
